# G1: half of the workgroups (alternating groups of 8) start the in-projection GEMM ~4 us late so the two halves' epilogue store bursts do not coincide
# baseline (speedup 1.0000x reference)
;     __device__ __forceinline__ bool next(int i, pg8::Unit& u) const { if (i >= DM / 256) return false; u.pm = c; u.pn = i; return true; }
;     __host__ __device__ bool next(int i, Unit& u) const {
;         const long L = (long)i * G + c; if (L >= nwg) return false;
; template <int PH>
; __device__ __forceinline__ void run_phase(LAS unsigned char* lds, int tid, int wid, int lane) {
;     ...
;             pg8::Gemm g{H, win_t + (size_t)l * WIN_ELEMS, MTOK, NPJ, DM}; pg8::StaticOrder S; S.init(MTOK, NPJ, (int)gridDim.x, (int)blockIdx.x);
;             EpiProj E{PJ, gate, a.in[9] + l * 4 * 768, a.in[10] + l * 768, (bf16*)(ws + WS_HALO)};
;             pg8::gemm_phase<EpiProj, pg8::StaticOrder, true, true>(lds, g, S, E);
.LBB0_101:
	s_cmp_gt_i32 s46, 2
	s_cselect_b64 s[0:1], -1, 0
	s_cmp_lt_i32 s47, 3
	v_writelane_b32 v249, s44, 2
	s_cselect_b64 s[4:5], -1, 0
	s_or_b64 s[0:1], s[0:1], s[4:5]
	v_writelane_b32 v249, s45, 3
	v_writelane_b32 v249, s46, 4
	v_writelane_b32 v249, s47, 5
	s_and_b64 vcc, exec, s[0:1]
	v_writelane_b32 v249, s84, 6
	s_nop 1
	v_writelane_b32 v249, s85, 7
	s_cbranch_vccnz .LBB0_183
	s_lshr_b32 s101, s2, 3
	s_and_b32 s101, s101, 1
	s_mul_i32 s101, s101, 10
	s_cmp_eq_u32 s101, 0
	s_cbranch_scc1 .Lstg_done1
.Lstg_loop1:
	s_sleep 16
	s_sub_u32 s101, s101, 1
	s_cmp_lg_u32 s101, 0
	s_cbranch_scc1 .Lstg_loop1
.Lstg_done1:
	s_mov_b64 s[4:5], s[84:85]
	v_mov_b32_e32 v8, v202
	s_cmpk_lt_i32 s2, 0x1100
	s_cselect_b64 s[0:1], -1, 0
	s_cmpk_gt_i32 s2, 0x10ff
	v_readfirstlane_b32 s6, v8
	s_cbranch_scc0 .LBB0_105
	s_load_dword s3, s[84:85], 0xa0
	s_andn2_b64 vcc, exec, s[0:1]
	s_cbranch_vccz .LBB0_106

; template <int PH>
; __device__ __forceinline__ void run_phase(LAS unsigned char* lds, int tid, int wid, int lane) {
;     ...
;             pg8::Gemm g{H, win_t + (size_t)l * WIN_ELEMS, MTOK, NPJ, DM}; pg8::StaticOrder S; S.init(MTOK, NPJ, (int)gridDim.x, (int)blockIdx.x);
;             EpiProj E{PJ, gate, a.in[9] + l * 4 * 768, a.in[10] + l * 768, (bf16*)(ws + WS_HALO)};
;             pg8::gemm_phase<EpiProj, pg8::StaticOrder, true, true>(lds, g, S, E);
.LBB0_626:
	s_cmp_gt_i32 s46, 6
	s_cselect_b64 s[0:1], -1, 0
	s_cmp_lt_i32 s47, 7
	s_cselect_b64 s[4:5], -1, 0
	s_or_b64 s[0:1], s[0:1], s[4:5]
	s_and_b64 vcc, exec, s[0:1]
	s_cbranch_vccnz .LBB0_708
	s_lshr_b32 s101, s2, 3
	s_and_b32 s101, s101, 1
	s_mul_i32 s101, s101, 10
	s_cmp_eq_u32 s101, 0
	s_cbranch_scc1 .Lstg_done2

;     __device__ __forceinline__ bool next(int i, pg8::Unit& u) const { if (i >= DM / 256) return false; u.pm = c; u.pn = i; return true; }
;     __host__ __device__ bool next(int i, Unit& u) const {
;         const long L = (long)i * G + c; if (L >= nwg) return false;
; template <int PH>
; __device__ __forceinline__ void run_phase(LAS unsigned char* lds, int tid, int wid, int lane) {
;     ...
;             pg8::Gemm g{H, win_t + (size_t)l * WIN_ELEMS, MTOK, NPJ, DM}; pg8::StaticOrder S; S.init(MTOK, NPJ, (int)gridDim.x, (int)blockIdx.x);
;             EpiProj E{PJ, gate, a.in[9] + l * 4 * 768, a.in[10] + l * 768, (bf16*)(ws + WS_HALO)};
;             pg8::gemm_phase<EpiProj, pg8::StaticOrder, true, true>(lds, g, S, E);
.Lstg_done2:
	s_mov_b64 s[4:5], s[84:85]
	s_waitcnt vmcnt(0)
	v_mov_b32_e32 v8, v202
	s_cmpk_lt_i32 s2, 0x1100
	s_cselect_b64 s[0:1], -1, 0
	s_cmpk_gt_i32 s2, 0x10ff
	v_readfirstlane_b32 s6, v8
	s_cbranch_scc0 .LBB0_630
	s_waitcnt lgkmcnt(0)
	s_load_dword s3, s[84:85], 0xa0
	s_andn2_b64 vcc, exec, s[0:1]
	s_cbranch_vccz .LBB0_631
